# ACT stores in the gate/up epilogue carry the nt cache hint (streaming data read once by the next phase)
# speedup vs baseline: 1.0100x; 1.0100x over previous
.LBB0_961:
	s_ashr_i32 s27, s26, 31
	s_lshl_b64 s[26:27], s[26:27], 19
	s_add_u32 s21, s57, s26
	s_addc_u32 s30, s58, s27
	s_ashr_i32 s29, s28, 31
	s_lshl_b64 s[26:27], s[28:29], 7
	s_add_u32 s21, s21, s26
	s_addc_u32 s27, s30, s27
	s_add_u32 s26, s21, s59
	s_addc_u32 s27, s27, 0
	s_mov_b32 s98, 0x44800000
	s_mov_b32 s99, 0x44800000
	v_pk_mul_f32 v[64:65], v[120:121], s[10:11] op_sel_hi:[1,0]
	v_pk_mul_f32 v[66:67], v[122:123], s[10:11] op_sel_hi:[1,0]
	v_pk_mul_f32 v[68:69], v[112:113], s[10:11] op_sel_hi:[1,0]
	v_pk_mul_f32 v[70:71], v[114:115], s[10:11] op_sel_hi:[1,0]
	v_exp_f32_e32 v64, v64
	v_exp_f32_e32 v65, v65
	v_exp_f32_e32 v66, v66
	v_exp_f32_e32 v67, v67
	v_exp_f32_e32 v68, v68
	v_exp_f32_e32 v69, v69
	v_exp_f32_e32 v70, v70
	v_exp_f32_e32 v71, v71
	v_pk_fma_f32 v[64:65], v[64:65], s[98:99], s[98:99]
	v_pk_fma_f32 v[66:67], v[66:67], s[98:99], s[98:99]
	v_pk_fma_f32 v[68:69], v[68:69], s[98:99], s[98:99]
	v_pk_fma_f32 v[70:71], v[70:71], s[98:99], s[98:99]
	v_rcp_f32_e32 v64, v64
	v_rcp_f32_e32 v65, v65
	v_pk_mul_f32 v[120:121], v[120:121], v[124:125]
	v_rcp_f32_e32 v66, v66
	v_rcp_f32_e32 v67, v67
	v_pk_mul_f32 v[122:123], v[122:123], v[126:127]
	v_rcp_f32_e32 v68, v68
	v_rcp_f32_e32 v69, v69
	v_pk_mul_f32 v[112:113], v[112:113], v[116:117]
	v_rcp_f32_e32 v70, v70
	v_rcp_f32_e32 v71, v71
	v_pk_mul_f32 v[114:115], v[114:115], v[118:119]
	v_add_u32_e32 v124, v128, v134
	v_pk_mul_f32 v[120:121], v[120:121], v[64:65]
	v_pk_mul_f32 v[122:123], v[122:123], v[66:67]
	v_pk_mul_f32 v[112:113], v[112:113], v[68:69]
	v_pk_mul_f32 v[114:115], v[114:115], v[70:71]
	v_med3_f32 v120, v120, s68, v150
	v_med3_f32 v121, v121, s68, v150
	v_med3_f32 v122, v122, s68, v150
	v_med3_f32 v123, v123, s68, v150
	v_med3_f32 v112, v112, s68, v150
	v_med3_f32 v113, v113, s68, v150
	v_med3_f32 v114, v114, s68, v150
	v_med3_f32 v115, v115, s68, v150
	v_cvt_pk_fp8_f32 v136, v120, v121
	v_cvt_pk_fp8_f32 v137, v112, v113
	v_cvt_pk_fp8_f32 v136, v122, v123 op_sel:[0,0,1]
	v_cvt_pk_fp8_f32 v137, v114, v115 op_sel:[0,0,1]
	s_mov_b32 s100, s26
	s_mov_b32 s101, s27
	global_store_dwordx2 v124, v[136:137], s[100:101] nt
	v_pk_mul_f32 v[64:65], v[104:105], s[10:11] op_sel_hi:[1,0]
	v_pk_mul_f32 v[66:67], v[106:107], s[10:11] op_sel_hi:[1,0]
	v_pk_mul_f32 v[68:69], v[96:97], s[10:11] op_sel_hi:[1,0]
	v_pk_mul_f32 v[70:71], v[98:99], s[10:11] op_sel_hi:[1,0]
	v_exp_f32_e32 v64, v64
	v_exp_f32_e32 v65, v65
	v_exp_f32_e32 v66, v66
	v_exp_f32_e32 v67, v67
	v_exp_f32_e32 v68, v68
	v_exp_f32_e32 v69, v69
	v_exp_f32_e32 v70, v70
	v_exp_f32_e32 v71, v71
	v_pk_fma_f32 v[64:65], v[64:65], s[98:99], s[98:99]
	v_pk_fma_f32 v[66:67], v[66:67], s[98:99], s[98:99]
	v_pk_fma_f32 v[68:69], v[68:69], s[98:99], s[98:99]
	v_pk_fma_f32 v[70:71], v[70:71], s[98:99], s[98:99]
	v_rcp_f32_e32 v64, v64
	v_rcp_f32_e32 v65, v65
	v_pk_mul_f32 v[104:105], v[104:105], v[108:109]
	v_rcp_f32_e32 v66, v66
	v_rcp_f32_e32 v67, v67
	v_pk_mul_f32 v[106:107], v[106:107], v[110:111]
	v_rcp_f32_e32 v68, v68
	v_rcp_f32_e32 v69, v69
	v_pk_mul_f32 v[96:97], v[96:97], v[100:101]
	v_rcp_f32_e32 v70, v70
	v_rcp_f32_e32 v71, v71
	v_pk_mul_f32 v[98:99], v[98:99], v[102:103]
	v_pk_mul_f32 v[104:105], v[104:105], v[64:65]
	v_pk_mul_f32 v[106:107], v[106:107], v[66:67]
	v_pk_mul_f32 v[96:97], v[96:97], v[68:69]
	v_pk_mul_f32 v[98:99], v[98:99], v[70:71]
	v_med3_f32 v104, v104, s68, v150
	v_med3_f32 v105, v105, s68, v150
	v_med3_f32 v106, v106, s68, v150
	v_med3_f32 v107, v107, s68, v150
	v_med3_f32 v96, v96, s68, v150
	v_med3_f32 v97, v97, s68, v150
	v_med3_f32 v98, v98, s68, v150
	v_med3_f32 v99, v99, s68, v150
	v_cvt_pk_fp8_f32 v140, v104, v105
	v_cvt_pk_fp8_f32 v141, v96, v97
	v_cvt_pk_fp8_f32 v140, v106, v107 op_sel:[0,0,1]
	v_cvt_pk_fp8_f32 v141, v98, v99 op_sel:[0,0,1]
	s_add_u32 s100, s26, 0x8000
	s_addc_u32 s101, s27, 0
	global_store_dwordx2 v124, v[140:141], s[100:101] nt
	v_pk_mul_f32 v[64:65], v[88:89], s[10:11] op_sel_hi:[1,0]
	v_pk_mul_f32 v[66:67], v[90:91], s[10:11] op_sel_hi:[1,0]
	v_pk_mul_f32 v[68:69], v[80:81], s[10:11] op_sel_hi:[1,0]
	v_pk_mul_f32 v[70:71], v[82:83], s[10:11] op_sel_hi:[1,0]
	v_exp_f32_e32 v64, v64
	v_exp_f32_e32 v65, v65
	v_exp_f32_e32 v66, v66
	v_exp_f32_e32 v67, v67
	v_exp_f32_e32 v68, v68
	v_exp_f32_e32 v69, v69
	v_exp_f32_e32 v70, v70
	v_exp_f32_e32 v71, v71
	v_pk_fma_f32 v[64:65], v[64:65], s[98:99], s[98:99]
	v_pk_fma_f32 v[66:67], v[66:67], s[98:99], s[98:99]
	v_pk_fma_f32 v[68:69], v[68:69], s[98:99], s[98:99]
	v_pk_fma_f32 v[70:71], v[70:71], s[98:99], s[98:99]
	v_rcp_f32_e32 v64, v64
	v_rcp_f32_e32 v65, v65
	v_pk_mul_f32 v[88:89], v[88:89], v[92:93]
	v_rcp_f32_e32 v66, v66
	v_rcp_f32_e32 v67, v67
	v_pk_mul_f32 v[90:91], v[90:91], v[94:95]
	v_rcp_f32_e32 v68, v68
	v_rcp_f32_e32 v69, v69
	v_pk_mul_f32 v[80:81], v[80:81], v[84:85]
	v_rcp_f32_e32 v70, v70
	v_rcp_f32_e32 v71, v71
	v_pk_mul_f32 v[82:83], v[82:83], v[86:87]
	v_pk_mul_f32 v[88:89], v[88:89], v[64:65]
	v_pk_mul_f32 v[90:91], v[90:91], v[66:67]
	v_pk_mul_f32 v[80:81], v[80:81], v[68:69]
	v_pk_mul_f32 v[82:83], v[82:83], v[70:71]
	v_med3_f32 v88, v88, s68, v150
	v_med3_f32 v89, v89, s68, v150
	v_med3_f32 v90, v90, s68, v150
	v_med3_f32 v91, v91, s68, v150
	v_med3_f32 v80, v80, s68, v150
	v_med3_f32 v81, v81, s68, v150
	v_med3_f32 v82, v82, s68, v150
	v_med3_f32 v83, v83, s68, v150
	v_cvt_pk_fp8_f32 v136, v88, v89
	v_cvt_pk_fp8_f32 v137, v80, v81
	v_cvt_pk_fp8_f32 v136, v90, v91 op_sel:[0,0,1]
	v_cvt_pk_fp8_f32 v137, v82, v83 op_sel:[0,0,1]
	s_add_u32 s100, s26, 0x10000
	s_addc_u32 s101, s27, 0
	global_store_dwordx2 v124, v[136:137], s[100:101] nt
	v_pk_mul_f32 v[64:65], v[72:73], s[10:11] op_sel_hi:[1,0]
	v_pk_mul_f32 v[66:67], v[74:75], s[10:11] op_sel_hi:[1,0]
	v_pk_mul_f32 v[68:69], v[230:231], s[10:11] op_sel_hi:[1,0]
	v_pk_mul_f32 v[70:71], v[232:233], s[10:11] op_sel_hi:[1,0]
	v_exp_f32_e32 v64, v64
	v_exp_f32_e32 v65, v65
	v_exp_f32_e32 v66, v66
	v_exp_f32_e32 v67, v67
	v_exp_f32_e32 v68, v68
	v_exp_f32_e32 v69, v69
	v_exp_f32_e32 v70, v70
	v_exp_f32_e32 v71, v71
	v_pk_fma_f32 v[64:65], v[64:65], s[98:99], s[98:99]
	v_pk_fma_f32 v[66:67], v[66:67], s[98:99], s[98:99]
	v_pk_fma_f32 v[68:69], v[68:69], s[98:99], s[98:99]
	v_pk_fma_f32 v[70:71], v[70:71], s[98:99], s[98:99]
	v_rcp_f32_e32 v64, v64
	v_rcp_f32_e32 v65, v65
	v_pk_mul_f32 v[72:73], v[72:73], v[76:77]
	v_rcp_f32_e32 v66, v66
	v_rcp_f32_e32 v67, v67
	v_pk_mul_f32 v[74:75], v[74:75], v[78:79]
	v_rcp_f32_e32 v68, v68
	v_rcp_f32_e32 v69, v69
	v_pk_mul_f32 v[230:231], v[230:231], v[20:21]
	v_rcp_f32_e32 v70, v70
	v_rcp_f32_e32 v71, v71
	v_pk_mul_f32 v[232:233], v[232:233], v[22:23]
	v_pk_mul_f32 v[72:73], v[72:73], v[64:65]
	v_pk_mul_f32 v[74:75], v[74:75], v[66:67]
	v_pk_mul_f32 v[230:231], v[230:231], v[68:69]
	v_pk_mul_f32 v[232:233], v[232:233], v[70:71]
	v_med3_f32 v72, v72, s68, v150
	v_med3_f32 v73, v73, s68, v150
	v_med3_f32 v74, v74, s68, v150
	v_med3_f32 v75, v75, s68, v150
	v_med3_f32 v230, v230, s68, v150
	v_med3_f32 v231, v231, s68, v150
	v_med3_f32 v232, v232, s68, v150
	v_med3_f32 v233, v233, s68, v150
	v_cvt_pk_fp8_f32 v140, v72, v73
	v_cvt_pk_fp8_f32 v141, v230, v231
	v_cvt_pk_fp8_f32 v140, v74, v75 op_sel:[0,0,1]
	v_cvt_pk_fp8_f32 v141, v232, v233 op_sel:[0,0,1]
	s_add_u32 s100, s26, 0x18000
	s_addc_u32 s101, s27, 0
	global_store_dwordx2 v124, v[140:141], s[100:101] nt
	v_pk_mul_f32 v[64:65], v[56:57], s[10:11] op_sel_hi:[1,0]
	v_pk_mul_f32 v[66:67], v[58:59], s[10:11] op_sel_hi:[1,0]
	v_pk_mul_f32 v[68:69], v[48:49], s[10:11] op_sel_hi:[1,0]
	v_pk_mul_f32 v[70:71], v[50:51], s[10:11] op_sel_hi:[1,0]
	v_exp_f32_e32 v64, v64
	v_exp_f32_e32 v65, v65
	v_exp_f32_e32 v66, v66
	v_exp_f32_e32 v67, v67
	v_exp_f32_e32 v68, v68
	v_exp_f32_e32 v69, v69
	v_exp_f32_e32 v70, v70
	v_exp_f32_e32 v71, v71
	v_pk_fma_f32 v[64:65], v[64:65], s[98:99], s[98:99]
	v_pk_fma_f32 v[66:67], v[66:67], s[98:99], s[98:99]
	v_pk_fma_f32 v[68:69], v[68:69], s[98:99], s[98:99]
	v_pk_fma_f32 v[70:71], v[70:71], s[98:99], s[98:99]
	v_rcp_f32_e32 v64, v64
	v_rcp_f32_e32 v65, v65
	v_pk_mul_f32 v[56:57], v[56:57], v[60:61]
	v_rcp_f32_e32 v66, v66
	v_rcp_f32_e32 v67, v67
	v_pk_mul_f32 v[58:59], v[58:59], v[62:63]
	v_rcp_f32_e32 v68, v68
	v_rcp_f32_e32 v69, v69
	v_pk_mul_f32 v[48:49], v[48:49], v[52:53]
	v_rcp_f32_e32 v70, v70
	v_rcp_f32_e32 v71, v71
	v_pk_mul_f32 v[50:51], v[50:51], v[54:55]
	v_pk_mul_f32 v[56:57], v[56:57], v[64:65]
	v_pk_mul_f32 v[58:59], v[58:59], v[66:67]
	v_pk_mul_f32 v[48:49], v[48:49], v[68:69]
	v_pk_mul_f32 v[50:51], v[50:51], v[70:71]
	v_med3_f32 v56, v56, s68, v150
	v_med3_f32 v57, v57, s68, v150
	v_med3_f32 v58, v58, s68, v150
	v_med3_f32 v59, v59, s68, v150
	v_med3_f32 v48, v48, s68, v150
	v_med3_f32 v49, v49, s68, v150
	v_med3_f32 v50, v50, s68, v150
	v_med3_f32 v51, v51, s68, v150
	v_cvt_pk_fp8_f32 v136, v56, v57
	v_cvt_pk_fp8_f32 v137, v48, v49
	v_cvt_pk_fp8_f32 v136, v58, v59 op_sel:[0,0,1]
	v_cvt_pk_fp8_f32 v137, v50, v51 op_sel:[0,0,1]
	s_add_u32 s100, s26, 0x40000
	s_addc_u32 s101, s27, 0
	global_store_dwordx2 v124, v[136:137], s[100:101] nt
	v_pk_mul_f32 v[64:65], v[40:41], s[10:11] op_sel_hi:[1,0]
	v_pk_mul_f32 v[66:67], v[42:43], s[10:11] op_sel_hi:[1,0]
	v_pk_mul_f32 v[68:69], v[32:33], s[10:11] op_sel_hi:[1,0]
	v_pk_mul_f32 v[70:71], v[34:35], s[10:11] op_sel_hi:[1,0]
	v_exp_f32_e32 v64, v64
	v_exp_f32_e32 v65, v65
	v_exp_f32_e32 v66, v66
	v_exp_f32_e32 v67, v67
	v_exp_f32_e32 v68, v68
	v_exp_f32_e32 v69, v69
	v_exp_f32_e32 v70, v70
	v_exp_f32_e32 v71, v71
	v_pk_fma_f32 v[64:65], v[64:65], s[98:99], s[98:99]
	v_pk_fma_f32 v[66:67], v[66:67], s[98:99], s[98:99]
	v_pk_fma_f32 v[68:69], v[68:69], s[98:99], s[98:99]
	v_pk_fma_f32 v[70:71], v[70:71], s[98:99], s[98:99]
	v_rcp_f32_e32 v64, v64
	v_rcp_f32_e32 v65, v65
	v_pk_mul_f32 v[40:41], v[40:41], v[44:45]
	v_rcp_f32_e32 v66, v66
	v_rcp_f32_e32 v67, v67
	v_pk_mul_f32 v[42:43], v[42:43], v[46:47]
	v_rcp_f32_e32 v68, v68
	v_rcp_f32_e32 v69, v69
	v_pk_mul_f32 v[32:33], v[32:33], v[36:37]
	v_rcp_f32_e32 v70, v70
	v_rcp_f32_e32 v71, v71
	v_pk_mul_f32 v[34:35], v[34:35], v[38:39]
	v_pk_mul_f32 v[40:41], v[40:41], v[64:65]
	v_pk_mul_f32 v[42:43], v[42:43], v[66:67]
	v_pk_mul_f32 v[32:33], v[32:33], v[68:69]
	v_pk_mul_f32 v[34:35], v[34:35], v[70:71]
	v_med3_f32 v40, v40, s68, v150
	v_med3_f32 v41, v41, s68, v150
	v_med3_f32 v42, v42, s68, v150
	v_med3_f32 v43, v43, s68, v150
	v_med3_f32 v32, v32, s68, v150
	v_med3_f32 v33, v33, s68, v150
	v_med3_f32 v34, v34, s68, v150
	v_med3_f32 v35, v35, s68, v150
	v_cvt_pk_fp8_f32 v140, v40, v41
	v_cvt_pk_fp8_f32 v141, v32, v33
	v_cvt_pk_fp8_f32 v140, v42, v43 op_sel:[0,0,1]
	v_cvt_pk_fp8_f32 v141, v34, v35 op_sel:[0,0,1]
	s_add_u32 s100, s26, 0x48000
	s_addc_u32 s101, s27, 0
	global_store_dwordx2 v124, v[140:141], s[100:101] nt
	v_pk_mul_f32 v[64:65], v[24:25], s[10:11] op_sel_hi:[1,0]
	v_pk_mul_f32 v[66:67], v[26:27], s[10:11] op_sel_hi:[1,0]
	v_pk_mul_f32 v[68:69], v[234:235], s[10:11] op_sel_hi:[1,0]
	v_pk_mul_f32 v[70:71], v[236:237], s[10:11] op_sel_hi:[1,0]
	v_exp_f32_e32 v64, v64
	v_exp_f32_e32 v65, v65
	v_exp_f32_e32 v66, v66
	v_exp_f32_e32 v67, v67
	v_exp_f32_e32 v68, v68
	v_exp_f32_e32 v69, v69
	v_exp_f32_e32 v70, v70
	v_exp_f32_e32 v71, v71
	v_pk_fma_f32 v[64:65], v[64:65], s[98:99], s[98:99]
	v_pk_fma_f32 v[66:67], v[66:67], s[98:99], s[98:99]
	v_pk_fma_f32 v[68:69], v[68:69], s[98:99], s[98:99]
	v_pk_fma_f32 v[70:71], v[70:71], s[98:99], s[98:99]
	v_rcp_f32_e32 v64, v64
	v_rcp_f32_e32 v65, v65
	v_pk_mul_f32 v[24:25], v[24:25], v[28:29]
	v_rcp_f32_e32 v66, v66
	v_rcp_f32_e32 v67, v67
	v_pk_mul_f32 v[26:27], v[26:27], v[30:31]
	v_rcp_f32_e32 v68, v68
	v_rcp_f32_e32 v69, v69
	v_pk_mul_f32 v[234:235], v[234:235], v[16:17]
	v_rcp_f32_e32 v70, v70
	v_rcp_f32_e32 v71, v71
	v_pk_mul_f32 v[236:237], v[236:237], v[18:19]
	v_pk_mul_f32 v[24:25], v[24:25], v[64:65]
	v_pk_mul_f32 v[26:27], v[26:27], v[66:67]
	v_pk_mul_f32 v[234:235], v[234:235], v[68:69]
	v_pk_mul_f32 v[236:237], v[236:237], v[70:71]
	v_med3_f32 v24, v24, s68, v150
	v_med3_f32 v25, v25, s68, v150
	v_med3_f32 v26, v26, s68, v150
	v_med3_f32 v27, v27, s68, v150
	v_med3_f32 v234, v234, s68, v150
	v_med3_f32 v235, v235, s68, v150
	v_med3_f32 v236, v236, s68, v150
	v_med3_f32 v237, v237, s68, v150
	v_cvt_pk_fp8_f32 v136, v24, v25
	v_cvt_pk_fp8_f32 v137, v234, v235
	v_cvt_pk_fp8_f32 v136, v26, v27 op_sel:[0,0,1]
	v_cvt_pk_fp8_f32 v137, v236, v237 op_sel:[0,0,1]
	s_add_u32 s100, s26, 0x50000
	s_addc_u32 s101, s27, 0
	global_store_dwordx2 v124, v[136:137], s[100:101] nt
	v_pk_mul_f32 v[64:65], v[8:9], s[10:11] op_sel_hi:[1,0]
	v_pk_mul_f32 v[66:67], v[10:11], s[10:11] op_sel_hi:[1,0]
	v_pk_mul_f32 v[68:69], v[0:1], s[10:11] op_sel_hi:[1,0]
	v_pk_mul_f32 v[70:71], v[2:3], s[10:11] op_sel_hi:[1,0]
	v_exp_f32_e32 v64, v64
	v_exp_f32_e32 v65, v65
	v_exp_f32_e32 v66, v66
	v_exp_f32_e32 v67, v67
	v_exp_f32_e32 v68, v68
	v_exp_f32_e32 v69, v69
	v_exp_f32_e32 v70, v70
	v_exp_f32_e32 v71, v71
	v_pk_fma_f32 v[64:65], v[64:65], s[98:99], s[98:99]
	v_pk_fma_f32 v[66:67], v[66:67], s[98:99], s[98:99]
	v_pk_fma_f32 v[68:69], v[68:69], s[98:99], s[98:99]
	v_pk_fma_f32 v[70:71], v[70:71], s[98:99], s[98:99]
	v_rcp_f32_e32 v64, v64
	v_rcp_f32_e32 v65, v65
	v_pk_mul_f32 v[8:9], v[8:9], v[12:13]
	v_rcp_f32_e32 v66, v66
	v_rcp_f32_e32 v67, v67
	v_pk_mul_f32 v[10:11], v[10:11], v[14:15]
	v_rcp_f32_e32 v68, v68
	v_rcp_f32_e32 v69, v69
	v_pk_mul_f32 v[0:1], v[0:1], v[4:5]
	v_rcp_f32_e32 v70, v70
	v_rcp_f32_e32 v71, v71
	v_pk_mul_f32 v[2:3], v[2:3], v[6:7]
	v_pk_mul_f32 v[8:9], v[8:9], v[64:65]
	v_pk_mul_f32 v[10:11], v[10:11], v[66:67]
	v_pk_mul_f32 v[0:1], v[0:1], v[68:69]
	v_pk_mul_f32 v[2:3], v[2:3], v[70:71]
	v_med3_f32 v8, v8, s68, v150
	v_med3_f32 v9, v9, s68, v150
	v_med3_f32 v10, v10, s68, v150
	v_med3_f32 v11, v11, s68, v150
	v_med3_f32 v0, v0, s68, v150
	v_med3_f32 v1, v1, s68, v150
	v_med3_f32 v2, v2, s68, v150
	v_med3_f32 v3, v3, s68, v150
	v_cvt_pk_fp8_f32 v140, v8, v9
	v_cvt_pk_fp8_f32 v141, v0, v1
	v_cvt_pk_fp8_f32 v140, v10, v11 op_sel:[0,0,1]
	v_cvt_pk_fp8_f32 v141, v2, v3 op_sel:[0,0,1]
	s_add_u32 s100, s26, 0x58000
	s_addc_u32 s101, s27, 0
	global_store_dwordx2 v124, v[140:141], s[100:101] nt
	s_andn2_b64 vcc, exec, s[4:5]
	s_cbranch_vccnz .LBB0_964
	v_mov_b32_e32 v4, s72
	ds_read_b128 v[120:123], v4
	ds_read_b128 v[112:115], v4
	ds_read_b128 v[104:107], v4
	ds_read_b128 v[96:99], v4
	ds_read_b128 v[88:91], v4
	ds_read_b128 v[80:83], v4
	ds_read_b128 v[72:75], v4
	ds_read_b128 v[230:233], v4
	ds_read_b128 v[124:127], v4
	ds_read_b128 v[116:119], v4
	ds_read_b128 v[108:111], v4
	ds_read_b128 v[100:103], v4
	ds_read_b128 v[92:95], v4
	ds_read_b128 v[84:87], v4
	ds_read_b128 v[76:79], v4
	ds_read_b128 v[20:23], v4
	ds_read_b128 v[56:59], v4
	ds_read_b128 v[48:51], v4
	ds_read_b128 v[40:43], v4
	ds_read_b128 v[32:35], v4
	ds_read_b128 v[24:27], v4
	ds_read_b128 v[234:237], v4
	ds_read_b128 v[8:11], v4
	ds_read_b128 v[0:3], v4
	ds_read_b128 v[60:63], v4
	ds_read_b128 v[52:55], v4
	ds_read_b128 v[44:47], v4
	ds_read_b128 v[36:39], v4
	ds_read_b128 v[28:31], v4
	ds_read_b128 v[16:19], v4
	ds_read_b128 v[12:15], v4
	ds_read_b128 v[4:7], v4
	ds_read2st64_b32 v[142:143], v143 offset1:2
	ds_read2st64_b32 v[144:145], v145 offset1:2
	s_andn2_b64 vcc, exec, s[14:15]
	s_cbranch_vccnz .LBB0_953
	s_barrier
	s_branch .LBB0_953

.LBB0_1875:
	s_ashr_i32 s27, s26, 31
	s_lshl_b64 s[26:27], s[26:27], 19
	s_add_u32 s21, s56, s26
	s_addc_u32 s30, s57, s27
	s_ashr_i32 s29, s28, 31
	s_lshl_b64 s[26:27], s[28:29], 7
	s_add_u32 s21, s21, s26
	s_addc_u32 s27, s30, s27
	s_add_u32 s26, s21, s58
	s_addc_u32 s27, s27, 0
	s_mov_b32 s98, 0x44800000
	s_mov_b32 s99, 0x44800000
	v_pk_mul_f32 v[64:65], v[120:121], s[10:11] op_sel_hi:[1,0]
	v_pk_mul_f32 v[66:67], v[122:123], s[10:11] op_sel_hi:[1,0]
	v_pk_mul_f32 v[68:69], v[112:113], s[10:11] op_sel_hi:[1,0]
	v_pk_mul_f32 v[70:71], v[114:115], s[10:11] op_sel_hi:[1,0]
	v_exp_f32_e32 v64, v64
	v_exp_f32_e32 v65, v65
	v_exp_f32_e32 v66, v66
	v_exp_f32_e32 v67, v67
	v_exp_f32_e32 v68, v68
	v_exp_f32_e32 v69, v69
	v_exp_f32_e32 v70, v70
	v_exp_f32_e32 v71, v71
	v_pk_fma_f32 v[64:65], v[64:65], s[98:99], s[98:99]
	v_pk_fma_f32 v[66:67], v[66:67], s[98:99], s[98:99]
	v_pk_fma_f32 v[68:69], v[68:69], s[98:99], s[98:99]
	v_pk_fma_f32 v[70:71], v[70:71], s[98:99], s[98:99]
	v_rcp_f32_e32 v64, v64
	v_rcp_f32_e32 v65, v65
	v_pk_mul_f32 v[120:121], v[120:121], v[124:125]
	v_rcp_f32_e32 v66, v66
	v_rcp_f32_e32 v67, v67
	v_pk_mul_f32 v[122:123], v[122:123], v[126:127]
	v_rcp_f32_e32 v68, v68
	v_rcp_f32_e32 v69, v69
	v_pk_mul_f32 v[112:113], v[112:113], v[116:117]
	v_rcp_f32_e32 v70, v70
	v_rcp_f32_e32 v71, v71
	v_pk_mul_f32 v[114:115], v[114:115], v[118:119]
	v_add_u32_e32 v124, v128, v134
	v_pk_mul_f32 v[120:121], v[120:121], v[64:65]
	v_pk_mul_f32 v[122:123], v[122:123], v[66:67]
	v_pk_mul_f32 v[112:113], v[112:113], v[68:69]
	v_pk_mul_f32 v[114:115], v[114:115], v[70:71]
	v_med3_f32 v120, v120, s67, v150
	v_med3_f32 v121, v121, s67, v150
	v_med3_f32 v122, v122, s67, v150
	v_med3_f32 v123, v123, s67, v150
	v_med3_f32 v112, v112, s67, v150
	v_med3_f32 v113, v113, s67, v150
	v_med3_f32 v114, v114, s67, v150
	v_med3_f32 v115, v115, s67, v150
	v_cvt_pk_fp8_f32 v136, v120, v121
	v_cvt_pk_fp8_f32 v137, v112, v113
	v_cvt_pk_fp8_f32 v136, v122, v123 op_sel:[0,0,1]
	v_cvt_pk_fp8_f32 v137, v114, v115 op_sel:[0,0,1]
	s_mov_b32 s100, s26
	s_mov_b32 s101, s27
	global_store_dwordx2 v124, v[136:137], s[100:101] nt
	v_pk_mul_f32 v[64:65], v[104:105], s[10:11] op_sel_hi:[1,0]
	v_pk_mul_f32 v[66:67], v[106:107], s[10:11] op_sel_hi:[1,0]
	v_pk_mul_f32 v[68:69], v[96:97], s[10:11] op_sel_hi:[1,0]
	v_pk_mul_f32 v[70:71], v[98:99], s[10:11] op_sel_hi:[1,0]
	v_exp_f32_e32 v64, v64
	v_exp_f32_e32 v65, v65
	v_exp_f32_e32 v66, v66
	v_exp_f32_e32 v67, v67
	v_exp_f32_e32 v68, v68
	v_exp_f32_e32 v69, v69
	v_exp_f32_e32 v70, v70
	v_exp_f32_e32 v71, v71
	v_pk_fma_f32 v[64:65], v[64:65], s[98:99], s[98:99]
	v_pk_fma_f32 v[66:67], v[66:67], s[98:99], s[98:99]
	v_pk_fma_f32 v[68:69], v[68:69], s[98:99], s[98:99]
	v_pk_fma_f32 v[70:71], v[70:71], s[98:99], s[98:99]
	v_rcp_f32_e32 v64, v64
	v_rcp_f32_e32 v65, v65
	v_pk_mul_f32 v[104:105], v[104:105], v[108:109]
	v_rcp_f32_e32 v66, v66
	v_rcp_f32_e32 v67, v67
	v_pk_mul_f32 v[106:107], v[106:107], v[110:111]
	v_rcp_f32_e32 v68, v68
	v_rcp_f32_e32 v69, v69
	v_pk_mul_f32 v[96:97], v[96:97], v[100:101]
	v_rcp_f32_e32 v70, v70
	v_rcp_f32_e32 v71, v71
	v_pk_mul_f32 v[98:99], v[98:99], v[102:103]
	v_pk_mul_f32 v[104:105], v[104:105], v[64:65]
	v_pk_mul_f32 v[106:107], v[106:107], v[66:67]
	v_pk_mul_f32 v[96:97], v[96:97], v[68:69]
	v_pk_mul_f32 v[98:99], v[98:99], v[70:71]
	v_med3_f32 v104, v104, s67, v150
	v_med3_f32 v105, v105, s67, v150
	v_med3_f32 v106, v106, s67, v150
	v_med3_f32 v107, v107, s67, v150
	v_med3_f32 v96, v96, s67, v150
	v_med3_f32 v97, v97, s67, v150
	v_med3_f32 v98, v98, s67, v150
	v_med3_f32 v99, v99, s67, v150
	v_cvt_pk_fp8_f32 v140, v104, v105
	v_cvt_pk_fp8_f32 v141, v96, v97
	v_cvt_pk_fp8_f32 v140, v106, v107 op_sel:[0,0,1]
	v_cvt_pk_fp8_f32 v141, v98, v99 op_sel:[0,0,1]
	s_add_u32 s100, s26, 0x8000
	s_addc_u32 s101, s27, 0
	global_store_dwordx2 v124, v[140:141], s[100:101] nt
	v_pk_mul_f32 v[64:65], v[88:89], s[10:11] op_sel_hi:[1,0]
	v_pk_mul_f32 v[66:67], v[90:91], s[10:11] op_sel_hi:[1,0]
	v_pk_mul_f32 v[68:69], v[80:81], s[10:11] op_sel_hi:[1,0]
	v_pk_mul_f32 v[70:71], v[82:83], s[10:11] op_sel_hi:[1,0]
	v_exp_f32_e32 v64, v64
	v_exp_f32_e32 v65, v65
	v_exp_f32_e32 v66, v66
	v_exp_f32_e32 v67, v67
	v_exp_f32_e32 v68, v68
	v_exp_f32_e32 v69, v69
	v_exp_f32_e32 v70, v70
	v_exp_f32_e32 v71, v71
	v_pk_fma_f32 v[64:65], v[64:65], s[98:99], s[98:99]
	v_pk_fma_f32 v[66:67], v[66:67], s[98:99], s[98:99]
	v_pk_fma_f32 v[68:69], v[68:69], s[98:99], s[98:99]
	v_pk_fma_f32 v[70:71], v[70:71], s[98:99], s[98:99]
	v_rcp_f32_e32 v64, v64
	v_rcp_f32_e32 v65, v65
	v_pk_mul_f32 v[88:89], v[88:89], v[92:93]
	v_rcp_f32_e32 v66, v66
	v_rcp_f32_e32 v67, v67
	v_pk_mul_f32 v[90:91], v[90:91], v[94:95]
	v_rcp_f32_e32 v68, v68
	v_rcp_f32_e32 v69, v69
	v_pk_mul_f32 v[80:81], v[80:81], v[84:85]
	v_rcp_f32_e32 v70, v70
	v_rcp_f32_e32 v71, v71
	v_pk_mul_f32 v[82:83], v[82:83], v[86:87]
	v_pk_mul_f32 v[88:89], v[88:89], v[64:65]
	v_pk_mul_f32 v[90:91], v[90:91], v[66:67]
	v_pk_mul_f32 v[80:81], v[80:81], v[68:69]
	v_pk_mul_f32 v[82:83], v[82:83], v[70:71]
	v_med3_f32 v88, v88, s67, v150
	v_med3_f32 v89, v89, s67, v150
	v_med3_f32 v90, v90, s67, v150
	v_med3_f32 v91, v91, s67, v150
	v_med3_f32 v80, v80, s67, v150
	v_med3_f32 v81, v81, s67, v150
	v_med3_f32 v82, v82, s67, v150
	v_med3_f32 v83, v83, s67, v150
	v_cvt_pk_fp8_f32 v136, v88, v89
	v_cvt_pk_fp8_f32 v137, v80, v81
	v_cvt_pk_fp8_f32 v136, v90, v91 op_sel:[0,0,1]
	v_cvt_pk_fp8_f32 v137, v82, v83 op_sel:[0,0,1]
	s_add_u32 s100, s26, 0x10000
	s_addc_u32 s101, s27, 0
	global_store_dwordx2 v124, v[136:137], s[100:101] nt
	v_pk_mul_f32 v[64:65], v[72:73], s[10:11] op_sel_hi:[1,0]
	v_pk_mul_f32 v[66:67], v[74:75], s[10:11] op_sel_hi:[1,0]
	v_pk_mul_f32 v[68:69], v[230:231], s[10:11] op_sel_hi:[1,0]
	v_pk_mul_f32 v[70:71], v[232:233], s[10:11] op_sel_hi:[1,0]
	v_exp_f32_e32 v64, v64
	v_exp_f32_e32 v65, v65
	v_exp_f32_e32 v66, v66
	v_exp_f32_e32 v67, v67
	v_exp_f32_e32 v68, v68
	v_exp_f32_e32 v69, v69
	v_exp_f32_e32 v70, v70
	v_exp_f32_e32 v71, v71
	v_pk_fma_f32 v[64:65], v[64:65], s[98:99], s[98:99]
	v_pk_fma_f32 v[66:67], v[66:67], s[98:99], s[98:99]
	v_pk_fma_f32 v[68:69], v[68:69], s[98:99], s[98:99]
	v_pk_fma_f32 v[70:71], v[70:71], s[98:99], s[98:99]
	v_rcp_f32_e32 v64, v64
	v_rcp_f32_e32 v65, v65
	v_pk_mul_f32 v[72:73], v[72:73], v[76:77]
	v_rcp_f32_e32 v66, v66
	v_rcp_f32_e32 v67, v67
	v_pk_mul_f32 v[74:75], v[74:75], v[78:79]
	v_rcp_f32_e32 v68, v68
	v_rcp_f32_e32 v69, v69
	v_pk_mul_f32 v[230:231], v[230:231], v[20:21]
	v_rcp_f32_e32 v70, v70
	v_rcp_f32_e32 v71, v71
	v_pk_mul_f32 v[232:233], v[232:233], v[22:23]
	v_pk_mul_f32 v[72:73], v[72:73], v[64:65]
	v_pk_mul_f32 v[74:75], v[74:75], v[66:67]
	v_pk_mul_f32 v[230:231], v[230:231], v[68:69]
	v_pk_mul_f32 v[232:233], v[232:233], v[70:71]
	v_med3_f32 v72, v72, s67, v150
	v_med3_f32 v73, v73, s67, v150
	v_med3_f32 v74, v74, s67, v150
	v_med3_f32 v75, v75, s67, v150
	v_med3_f32 v230, v230, s67, v150
	v_med3_f32 v231, v231, s67, v150
	v_med3_f32 v232, v232, s67, v150
	v_med3_f32 v233, v233, s67, v150
	v_cvt_pk_fp8_f32 v140, v72, v73
	v_cvt_pk_fp8_f32 v141, v230, v231
	v_cvt_pk_fp8_f32 v140, v74, v75 op_sel:[0,0,1]
	v_cvt_pk_fp8_f32 v141, v232, v233 op_sel:[0,0,1]
	s_add_u32 s100, s26, 0x18000
	s_addc_u32 s101, s27, 0
	global_store_dwordx2 v124, v[140:141], s[100:101] nt
	v_pk_mul_f32 v[64:65], v[56:57], s[10:11] op_sel_hi:[1,0]
	v_pk_mul_f32 v[66:67], v[58:59], s[10:11] op_sel_hi:[1,0]
	v_pk_mul_f32 v[68:69], v[48:49], s[10:11] op_sel_hi:[1,0]
	v_pk_mul_f32 v[70:71], v[50:51], s[10:11] op_sel_hi:[1,0]
	v_exp_f32_e32 v64, v64
	v_exp_f32_e32 v65, v65
	v_exp_f32_e32 v66, v66
	v_exp_f32_e32 v67, v67
	v_exp_f32_e32 v68, v68
	v_exp_f32_e32 v69, v69
	v_exp_f32_e32 v70, v70
	v_exp_f32_e32 v71, v71
	v_pk_fma_f32 v[64:65], v[64:65], s[98:99], s[98:99]
	v_pk_fma_f32 v[66:67], v[66:67], s[98:99], s[98:99]
	v_pk_fma_f32 v[68:69], v[68:69], s[98:99], s[98:99]
	v_pk_fma_f32 v[70:71], v[70:71], s[98:99], s[98:99]
	v_rcp_f32_e32 v64, v64
	v_rcp_f32_e32 v65, v65
	v_pk_mul_f32 v[56:57], v[56:57], v[60:61]
	v_rcp_f32_e32 v66, v66
	v_rcp_f32_e32 v67, v67
	v_pk_mul_f32 v[58:59], v[58:59], v[62:63]
	v_rcp_f32_e32 v68, v68
	v_rcp_f32_e32 v69, v69
	v_pk_mul_f32 v[48:49], v[48:49], v[52:53]
	v_rcp_f32_e32 v70, v70
	v_rcp_f32_e32 v71, v71
	v_pk_mul_f32 v[50:51], v[50:51], v[54:55]
	v_pk_mul_f32 v[56:57], v[56:57], v[64:65]
	v_pk_mul_f32 v[58:59], v[58:59], v[66:67]
	v_pk_mul_f32 v[48:49], v[48:49], v[68:69]
	v_pk_mul_f32 v[50:51], v[50:51], v[70:71]
	v_med3_f32 v56, v56, s67, v150
	v_med3_f32 v57, v57, s67, v150
	v_med3_f32 v58, v58, s67, v150
	v_med3_f32 v59, v59, s67, v150
	v_med3_f32 v48, v48, s67, v150
	v_med3_f32 v49, v49, s67, v150
	v_med3_f32 v50, v50, s67, v150
	v_med3_f32 v51, v51, s67, v150
	v_cvt_pk_fp8_f32 v136, v56, v57
	v_cvt_pk_fp8_f32 v137, v48, v49
	v_cvt_pk_fp8_f32 v136, v58, v59 op_sel:[0,0,1]
	v_cvt_pk_fp8_f32 v137, v50, v51 op_sel:[0,0,1]
	s_add_u32 s100, s26, 0x40000
	s_addc_u32 s101, s27, 0
	global_store_dwordx2 v124, v[136:137], s[100:101] nt
	v_pk_mul_f32 v[64:65], v[40:41], s[10:11] op_sel_hi:[1,0]
	v_pk_mul_f32 v[66:67], v[42:43], s[10:11] op_sel_hi:[1,0]
	v_pk_mul_f32 v[68:69], v[32:33], s[10:11] op_sel_hi:[1,0]
	v_pk_mul_f32 v[70:71], v[34:35], s[10:11] op_sel_hi:[1,0]
	v_exp_f32_e32 v64, v64
	v_exp_f32_e32 v65, v65
	v_exp_f32_e32 v66, v66
	v_exp_f32_e32 v67, v67
	v_exp_f32_e32 v68, v68
	v_exp_f32_e32 v69, v69
	v_exp_f32_e32 v70, v70
	v_exp_f32_e32 v71, v71
	v_pk_fma_f32 v[64:65], v[64:65], s[98:99], s[98:99]
	v_pk_fma_f32 v[66:67], v[66:67], s[98:99], s[98:99]
	v_pk_fma_f32 v[68:69], v[68:69], s[98:99], s[98:99]
	v_pk_fma_f32 v[70:71], v[70:71], s[98:99], s[98:99]
	v_rcp_f32_e32 v64, v64
	v_rcp_f32_e32 v65, v65
	v_pk_mul_f32 v[40:41], v[40:41], v[44:45]
	v_rcp_f32_e32 v66, v66
	v_rcp_f32_e32 v67, v67
	v_pk_mul_f32 v[42:43], v[42:43], v[46:47]
	v_rcp_f32_e32 v68, v68
	v_rcp_f32_e32 v69, v69
	v_pk_mul_f32 v[32:33], v[32:33], v[36:37]
	v_rcp_f32_e32 v70, v70
	v_rcp_f32_e32 v71, v71
	v_pk_mul_f32 v[34:35], v[34:35], v[38:39]
	v_pk_mul_f32 v[40:41], v[40:41], v[64:65]
	v_pk_mul_f32 v[42:43], v[42:43], v[66:67]
	v_pk_mul_f32 v[32:33], v[32:33], v[68:69]
	v_pk_mul_f32 v[34:35], v[34:35], v[70:71]
	v_med3_f32 v40, v40, s67, v150
	v_med3_f32 v41, v41, s67, v150
	v_med3_f32 v42, v42, s67, v150
	v_med3_f32 v43, v43, s67, v150
	v_med3_f32 v32, v32, s67, v150
	v_med3_f32 v33, v33, s67, v150
	v_med3_f32 v34, v34, s67, v150
	v_med3_f32 v35, v35, s67, v150
	v_cvt_pk_fp8_f32 v140, v40, v41
	v_cvt_pk_fp8_f32 v141, v32, v33
	v_cvt_pk_fp8_f32 v140, v42, v43 op_sel:[0,0,1]
	v_cvt_pk_fp8_f32 v141, v34, v35 op_sel:[0,0,1]
	s_add_u32 s100, s26, 0x48000
	s_addc_u32 s101, s27, 0
	global_store_dwordx2 v124, v[140:141], s[100:101] nt
	v_pk_mul_f32 v[64:65], v[24:25], s[10:11] op_sel_hi:[1,0]
	v_pk_mul_f32 v[66:67], v[26:27], s[10:11] op_sel_hi:[1,0]
	v_pk_mul_f32 v[68:69], v[234:235], s[10:11] op_sel_hi:[1,0]
	v_pk_mul_f32 v[70:71], v[236:237], s[10:11] op_sel_hi:[1,0]
	v_exp_f32_e32 v64, v64
	v_exp_f32_e32 v65, v65
	v_exp_f32_e32 v66, v66
	v_exp_f32_e32 v67, v67
	v_exp_f32_e32 v68, v68
	v_exp_f32_e32 v69, v69
	v_exp_f32_e32 v70, v70
	v_exp_f32_e32 v71, v71
	v_pk_fma_f32 v[64:65], v[64:65], s[98:99], s[98:99]
	v_pk_fma_f32 v[66:67], v[66:67], s[98:99], s[98:99]
	v_pk_fma_f32 v[68:69], v[68:69], s[98:99], s[98:99]
	v_pk_fma_f32 v[70:71], v[70:71], s[98:99], s[98:99]
	v_rcp_f32_e32 v64, v64
	v_rcp_f32_e32 v65, v65
	v_pk_mul_f32 v[24:25], v[24:25], v[28:29]
	v_rcp_f32_e32 v66, v66
	v_rcp_f32_e32 v67, v67
	v_pk_mul_f32 v[26:27], v[26:27], v[30:31]
	v_rcp_f32_e32 v68, v68
	v_rcp_f32_e32 v69, v69
	v_pk_mul_f32 v[234:235], v[234:235], v[16:17]
	v_rcp_f32_e32 v70, v70
	v_rcp_f32_e32 v71, v71
	v_pk_mul_f32 v[236:237], v[236:237], v[18:19]
	v_pk_mul_f32 v[24:25], v[24:25], v[64:65]
	v_pk_mul_f32 v[26:27], v[26:27], v[66:67]
	v_pk_mul_f32 v[234:235], v[234:235], v[68:69]
	v_pk_mul_f32 v[236:237], v[236:237], v[70:71]
	v_med3_f32 v24, v24, s67, v150
	v_med3_f32 v25, v25, s67, v150
	v_med3_f32 v26, v26, s67, v150
	v_med3_f32 v27, v27, s67, v150
	v_med3_f32 v234, v234, s67, v150
	v_med3_f32 v235, v235, s67, v150
	v_med3_f32 v236, v236, s67, v150
	v_med3_f32 v237, v237, s67, v150
	v_cvt_pk_fp8_f32 v136, v24, v25
	v_cvt_pk_fp8_f32 v137, v234, v235
	v_cvt_pk_fp8_f32 v136, v26, v27 op_sel:[0,0,1]
	v_cvt_pk_fp8_f32 v137, v236, v237 op_sel:[0,0,1]
	s_add_u32 s100, s26, 0x50000
	s_addc_u32 s101, s27, 0
	global_store_dwordx2 v124, v[136:137], s[100:101] nt
	v_pk_mul_f32 v[64:65], v[8:9], s[10:11] op_sel_hi:[1,0]
	v_pk_mul_f32 v[66:67], v[10:11], s[10:11] op_sel_hi:[1,0]
	v_pk_mul_f32 v[68:69], v[0:1], s[10:11] op_sel_hi:[1,0]
	v_pk_mul_f32 v[70:71], v[2:3], s[10:11] op_sel_hi:[1,0]
	v_exp_f32_e32 v64, v64
	v_exp_f32_e32 v65, v65
	v_exp_f32_e32 v66, v66
	v_exp_f32_e32 v67, v67
	v_exp_f32_e32 v68, v68
	v_exp_f32_e32 v69, v69
	v_exp_f32_e32 v70, v70
	v_exp_f32_e32 v71, v71
	v_pk_fma_f32 v[64:65], v[64:65], s[98:99], s[98:99]
	v_pk_fma_f32 v[66:67], v[66:67], s[98:99], s[98:99]
	v_pk_fma_f32 v[68:69], v[68:69], s[98:99], s[98:99]
	v_pk_fma_f32 v[70:71], v[70:71], s[98:99], s[98:99]
	v_rcp_f32_e32 v64, v64
	v_rcp_f32_e32 v65, v65
	v_pk_mul_f32 v[8:9], v[8:9], v[12:13]
	v_rcp_f32_e32 v66, v66
	v_rcp_f32_e32 v67, v67
	v_pk_mul_f32 v[10:11], v[10:11], v[14:15]
	v_rcp_f32_e32 v68, v68
	v_rcp_f32_e32 v69, v69
	v_pk_mul_f32 v[0:1], v[0:1], v[4:5]
	v_rcp_f32_e32 v70, v70
	v_rcp_f32_e32 v71, v71
	v_pk_mul_f32 v[2:3], v[2:3], v[6:7]
	v_pk_mul_f32 v[8:9], v[8:9], v[64:65]
	v_pk_mul_f32 v[10:11], v[10:11], v[66:67]
	v_pk_mul_f32 v[0:1], v[0:1], v[68:69]
	v_pk_mul_f32 v[2:3], v[2:3], v[70:71]
	v_med3_f32 v8, v8, s67, v150
	v_med3_f32 v9, v9, s67, v150
	v_med3_f32 v10, v10, s67, v150
	v_med3_f32 v11, v11, s67, v150
	v_med3_f32 v0, v0, s67, v150
	v_med3_f32 v1, v1, s67, v150
	v_med3_f32 v2, v2, s67, v150
	v_med3_f32 v3, v3, s67, v150
	v_cvt_pk_fp8_f32 v140, v8, v9
	v_cvt_pk_fp8_f32 v141, v0, v1
	v_cvt_pk_fp8_f32 v140, v10, v11 op_sel:[0,0,1]
	v_cvt_pk_fp8_f32 v141, v2, v3 op_sel:[0,0,1]
	s_add_u32 s100, s26, 0x58000
	s_addc_u32 s101, s27, 0
	global_store_dwordx2 v124, v[140:141], s[100:101] nt
	s_andn2_b64 vcc, exec, s[4:5]
	s_cbranch_vccnz .LBB0_1878
	v_mov_b32_e32 v4, s71
	ds_read_b128 v[120:123], v4
	ds_read_b128 v[112:115], v4
	ds_read_b128 v[104:107], v4
	ds_read_b128 v[96:99], v4
	ds_read_b128 v[88:91], v4
	ds_read_b128 v[80:83], v4
	ds_read_b128 v[72:75], v4
	ds_read_b128 v[230:233], v4
	ds_read_b128 v[124:127], v4
	ds_read_b128 v[116:119], v4
	ds_read_b128 v[108:111], v4
	ds_read_b128 v[100:103], v4
	ds_read_b128 v[92:95], v4
	ds_read_b128 v[84:87], v4
	ds_read_b128 v[76:79], v4
	ds_read_b128 v[20:23], v4
	ds_read_b128 v[56:59], v4
	ds_read_b128 v[48:51], v4
	ds_read_b128 v[40:43], v4
	ds_read_b128 v[32:35], v4
	ds_read_b128 v[24:27], v4
	ds_read_b128 v[234:237], v4
	ds_read_b128 v[8:11], v4
	ds_read_b128 v[0:3], v4
	ds_read_b128 v[60:63], v4
	ds_read_b128 v[52:55], v4
	ds_read_b128 v[44:47], v4
	ds_read_b128 v[36:39], v4
	ds_read_b128 v[28:31], v4
	ds_read_b128 v[16:19], v4
	ds_read_b128 v[12:15], v4
	ds_read_b128 v[4:7], v4
	ds_read2st64_b32 v[142:143], v143 offset1:2
	ds_read2st64_b32 v[144:145], v145 offset1:2
	s_andn2_b64 vcc, exec, s[14:15]
	s_cbranch_vccnz .LBB0_1867
	s_barrier
	s_branch .LBB0_1867
